# hy_transpose: the block that only wave 0 needs (rows 64,65 of the tile) is branched over in the other waves instead of issued with an empty exec mask
# baseline (speedup 1.0000x reference)
; __device__ __forceinline__ u32x4 zero4() { unsigned z = 0; asm volatile("" : "+v"(z)); return (u32x4){z, z, z, z}; }
; __device__ __forceinline__ float lo_bf(unsigned w) { return __uint_as_float(w << 16); }
; __device__ __forceinline__ float hi_bf(unsigned w) { return __uint_as_float(w & 0xffff0000u); }
; __device__ void hy_transpose_phase(unsigned char* smem, const Params& p, int l) {
;     ...
;     for (int t = blockIdx.x; t < ntile; t += gridDim.x) {
;         const int cblk = t % (HYC / 64), rblk = t / (HYC / 64); const int b = rblk >> 5, t0 = (rblk & 31) * 64, c0 = cblk * 64;
;         __syncthreads();
;         for (int e = tid; e < 66 * 8; e += 512) { const int rr = e >> 3, c8 = e & 7; const int tt = t0 - 1 + rr;
;             u32x4 v = zero4();
;             if (tt >= 0 && tt < SEQ) v = *(const u32x4*)(uhy + ((size_t)b * SEQ + tt) * HYC + c0 + c8 * 8);
;             float* d = tile + rr * 65 + c8 * 8;
;             d[0] = lo_bf(v.x); d[1] = hi_bf(v.x); d[2] = lo_bf(v.y); d[3] = hi_bf(v.y); d[4] = lo_bf(v.z); d[5] = hi_bf(v.z); d[6] = lo_bf(v.w); d[7] = hi_bf(v.w); }
.Lhy3_top_0:
	s_mul_hi_i32 s12, s15, 0x2aaaaaab
	s_lshr_b32 s13, s12, 31
	s_ashr_i32 s20, s12, 2
	s_add_i32 s20, s20, s13
	s_ashr_i32 s12, s20, 5
	s_ashr_i32 s13, s12, 31
	s_mul_i32 s16, s20, 24
	s_sub_i32 s16, s15, s16
	s_lshl_b32 s17, s20, 6
	s_and_b32 s24, s17, 0x7c0
	s_lshl_b32 s16, s16, 6
	v_add_u32_e32 v48, s16, v10
	v_ashrrev_i32_e32 v49, 31, v48
	v_lshlrev_b64 v[48:49], 2, v[48:49]
	v_lshl_add_u64 v[46:47], s[8:9], 0, v[48:49]
	s_mov_b64 s[22:23], 0x1800
	global_load_dword v50, v[46:47], off
	v_lshl_add_u64 v[44:45], v[46:47], 0, s[22:23]
	s_mov_b64 s[22:23], 0x3000
	global_load_dword v52, v[44:45], off
	v_lshl_add_u64 v[44:45], v[46:47], 0, s[22:23]
	global_load_dword v54, v[44:45], off
	v_lshl_add_u64 v[44:45], s[10:11], 0, v[48:49]
	global_load_dword v56, v[44:45], off
	s_waitcnt vmcnt(10)
	v_mul_u32_u24_e32 v14, 0x104, v10
	v_add_u32_e32 v14, v14, v6
	v_lshlrev_b32_e32 v13, 16, v36
	v_and_b32_e32 v0, 0xffff0000, v36
	ds_write2_b32 v14, v13, v0 offset0:0 offset1:1
	v_lshlrev_b32_e32 v13, 16, v37
	v_and_b32_e32 v0, 0xffff0000, v37
	ds_write2_b32 v14, v13, v0 offset0:2 offset1:3
	v_lshlrev_b32_e32 v13, 16, v38
	v_and_b32_e32 v0, 0xffff0000, v38
	ds_write2_b32 v14, v13, v0 offset0:4 offset1:5
	v_lshlrev_b32_e32 v13, 16, v39
	v_and_b32_e32 v0, 0xffff0000, v39
	ds_write2_b32 v14, v13, v0 offset0:6 offset1:7
	v_cmp_gt_u32_e32 vcc, 16, v7
	s_and_saveexec_b64 s[28:29], vcc
	s_cbranch_execz .Lhy3_x0
	v_add_u32_e32 v14, 0x4100, v14
	v_lshlrev_b32_e32 v13, 16, v40
	v_and_b32_e32 v0, 0xffff0000, v40
	ds_write2_b32 v14, v13, v0 offset0:0 offset1:1
	v_lshlrev_b32_e32 v13, 16, v41
	v_and_b32_e32 v0, 0xffff0000, v41
	ds_write2_b32 v14, v13, v0 offset0:2 offset1:3
	v_lshlrev_b32_e32 v13, 16, v42
	v_and_b32_e32 v0, 0xffff0000, v42
	ds_write2_b32 v14, v13, v0 offset0:4 offset1:5
	v_lshlrev_b32_e32 v13, 16, v43
	v_and_b32_e32 v0, 0xffff0000, v43
	ds_write2_b32 v14, v13, v0 offset0:6 offset1:7
.Lhy3_x0:
	s_mov_b64 exec, s[28:29]
	s_lshl_b32 s98, s14, 1
	s_add_i32 s98, s98, s15
	s_cmpk_gt_i32 s98, 0x2fff
	s_cbranch_scc1 .Lhy3_nopf_0
	s_mul_hi_i32 s99, s98, 0x2aaaaaab
	s_lshr_b32 s100, s99, 31
	s_ashr_i32 s99, s99, 2
	s_add_i32 s99, s99, s100
	s_mul_i32 s100, s99, 24
	s_sub_i32 s100, s98, s100
	s_lshl_b32 s100, s100, 7
	s_lshl_b32 s101, s99, 6
	s_and_b32 s101, s101, 0x7c0
	s_add_i32 s101, s101, -1
	s_ashr_i32 s99, s99, 5
	s_lshl_b32 s99, s99, 11
	v_add_u32_e32 v44, s101, v10
	v_add_u32_e32 v45, s99, v44
	v_mul_u32_u24_e32 v45, 0xc00, v45
	v_add_u32_e32 v46, s100, v45
	v_mov_b32_e32 v47, 0
	v_mov_b32_e32 v36, 0
	v_mov_b32_e32 v37, 0
	v_mov_b32_e32 v38, 0
	v_mov_b32_e32 v39, 0
	v_lshl_add_u64 v[46:47], v[4:5], 0, v[46:47]
	v_cmp_gt_u32_e32 vcc, 0x800, v44
	s_and_saveexec_b64 s[28:29], vcc
	global_load_dwordx4 v[36:39], v[46:47], off
	s_mov_b64 exec, s[28:29]
	s_cmp_lt_u32 s31, 64
	s_cbranch_scc0 .Lhy3_p2_l0
	v_add_u32_e32 v44, 64, v44
	v_add_u32_e32 v45, s99, v44
	v_mul_u32_u24_e32 v45, 0xc00, v45
	v_add_u32_e32 v46, s100, v45
	v_mov_b32_e32 v47, 0
	v_mov_b32_e32 v40, 0
	v_mov_b32_e32 v41, 0
	v_mov_b32_e32 v42, 0
	v_mov_b32_e32 v43, 0
	v_lshl_add_u64 v[46:47], v[4:5], 0, v[46:47]
	v_cmp_gt_u32_e32 vcc, 0x800, v44
	v_cmp_gt_u32_e64 s[34:35], 16, v7
	s_and_b64 vcc, vcc, s[34:35]
	s_and_saveexec_b64 s[28:29], vcc
	global_load_dwordx4 v[40:43], v[46:47], off
	s_mov_b64 exec, s[28:29]

; __device__ __forceinline__ u32x4 zero4() { unsigned z = 0; asm volatile("" : "+v"(z)); return (u32x4){z, z, z, z}; }
; __device__ __forceinline__ float lo_bf(unsigned w) { return __uint_as_float(w << 16); }
; __device__ __forceinline__ float hi_bf(unsigned w) { return __uint_as_float(w & 0xffff0000u); }
; __device__ void hy_transpose_phase(unsigned char* smem, const Params& p, int l) {
;     ...
;     for (int t = blockIdx.x; t < ntile; t += gridDim.x) {
;         const int cblk = t % (HYC / 64), rblk = t / (HYC / 64); const int b = rblk >> 5, t0 = (rblk & 31) * 64, c0 = cblk * 64;
;         __syncthreads();
;         for (int e = tid; e < 66 * 8; e += 512) { const int rr = e >> 3, c8 = e & 7; const int tt = t0 - 1 + rr;
;             u32x4 v = zero4();
;             if (tt >= 0 && tt < SEQ) v = *(const u32x4*)(uhy + ((size_t)b * SEQ + tt) * HYC + c0 + c8 * 8);
;             float* d = tile + rr * 65 + c8 * 8;
;             d[0] = lo_bf(v.x); d[1] = hi_bf(v.x); d[2] = lo_bf(v.y); d[3] = hi_bf(v.y); d[4] = lo_bf(v.z); d[5] = hi_bf(v.z); d[6] = lo_bf(v.w); d[7] = hi_bf(v.w); }
.Lhy3_top_1:
	s_mul_hi_i32 s12, s15, 0x2aaaaaab
	s_lshr_b32 s13, s12, 31
	s_ashr_i32 s20, s12, 2
	s_add_i32 s20, s20, s13
	s_ashr_i32 s12, s20, 5
	s_ashr_i32 s13, s12, 31
	s_mul_i32 s16, s20, 24
	s_sub_i32 s16, s15, s16
	s_lshl_b32 s17, s20, 6
	s_and_b32 s24, s17, 0x7c0
	s_lshl_b32 s16, s16, 6
	v_add_u32_e32 v48, s16, v10
	v_ashrrev_i32_e32 v49, 31, v48
	v_lshlrev_b64 v[48:49], 2, v[48:49]
	v_lshl_add_u64 v[46:47], s[8:9], 0, v[48:49]
	s_mov_b64 s[22:23], 0x1800
	global_load_dword v50, v[46:47], off
	v_lshl_add_u64 v[44:45], v[46:47], 0, s[22:23]
	s_mov_b64 s[22:23], 0x3000
	global_load_dword v52, v[44:45], off
	v_lshl_add_u64 v[44:45], v[46:47], 0, s[22:23]
	global_load_dword v54, v[44:45], off
	v_lshl_add_u64 v[44:45], s[10:11], 0, v[48:49]
	global_load_dword v56, v[44:45], off
	s_waitcnt vmcnt(10)
	v_mul_u32_u24_e32 v14, 0x104, v10
	v_add_u32_e32 v14, v14, v6
	v_add_u32_e32 v14, 0x4400, v14
	v_lshlrev_b32_e32 v13, 16, v58
	v_and_b32_e32 v0, 0xffff0000, v58
	ds_write2_b32 v14, v13, v0 offset0:0 offset1:1
	v_lshlrev_b32_e32 v13, 16, v59
	v_and_b32_e32 v0, 0xffff0000, v59
	ds_write2_b32 v14, v13, v0 offset0:2 offset1:3
	v_lshlrev_b32_e32 v13, 16, v60
	v_and_b32_e32 v0, 0xffff0000, v60
	ds_write2_b32 v14, v13, v0 offset0:4 offset1:5
	v_lshlrev_b32_e32 v13, 16, v61
	v_and_b32_e32 v0, 0xffff0000, v61
	ds_write2_b32 v14, v13, v0 offset0:6 offset1:7
	v_cmp_gt_u32_e32 vcc, 16, v7
	s_and_saveexec_b64 s[28:29], vcc
	s_cbranch_execz .Lhy3_x1
	v_add_u32_e32 v14, 0x4100, v14
	v_lshlrev_b32_e32 v13, 16, v62
	v_and_b32_e32 v0, 0xffff0000, v62
	ds_write2_b32 v14, v13, v0 offset0:0 offset1:1
	v_lshlrev_b32_e32 v13, 16, v63
	v_and_b32_e32 v0, 0xffff0000, v63
	ds_write2_b32 v14, v13, v0 offset0:2 offset1:3
	v_lshlrev_b32_e32 v13, 16, v64
	v_and_b32_e32 v0, 0xffff0000, v64
	ds_write2_b32 v14, v13, v0 offset0:4 offset1:5
	v_lshlrev_b32_e32 v13, 16, v65
	v_and_b32_e32 v0, 0xffff0000, v65
	ds_write2_b32 v14, v13, v0 offset0:6 offset1:7
.Lhy3_x1:
	s_mov_b64 exec, s[28:29]
	s_lshl_b32 s98, s14, 1
	s_add_i32 s98, s98, s15
	s_cmpk_gt_i32 s98, 0x2fff
	s_cbranch_scc1 .Lhy3_nopf_1
	s_mul_hi_i32 s99, s98, 0x2aaaaaab
	s_lshr_b32 s100, s99, 31
	s_ashr_i32 s99, s99, 2
	s_add_i32 s99, s99, s100
	s_mul_i32 s100, s99, 24
	s_sub_i32 s100, s98, s100
	s_lshl_b32 s100, s100, 7
	s_lshl_b32 s101, s99, 6
	s_and_b32 s101, s101, 0x7c0
	s_add_i32 s101, s101, -1
	s_ashr_i32 s99, s99, 5
	s_lshl_b32 s99, s99, 11
	v_add_u32_e32 v44, s101, v10
	v_add_u32_e32 v45, s99, v44
	v_mul_u32_u24_e32 v45, 0xc00, v45
	v_add_u32_e32 v46, s100, v45
	v_mov_b32_e32 v47, 0
	v_mov_b32_e32 v58, 0
	v_mov_b32_e32 v59, 0
	v_mov_b32_e32 v60, 0
	v_mov_b32_e32 v61, 0
	v_lshl_add_u64 v[46:47], v[4:5], 0, v[46:47]
	v_cmp_gt_u32_e32 vcc, 0x800, v44
	s_and_saveexec_b64 s[28:29], vcc
	global_load_dwordx4 v[58:61], v[46:47], off
	s_mov_b64 exec, s[28:29]
	s_cmp_lt_u32 s31, 64
	s_cbranch_scc0 .Lhy3_p2_l1
	v_add_u32_e32 v44, 64, v44
	v_add_u32_e32 v45, s99, v44
	v_mul_u32_u24_e32 v45, 0xc00, v45
	v_add_u32_e32 v46, s100, v45
	v_mov_b32_e32 v47, 0
	v_mov_b32_e32 v62, 0
	v_mov_b32_e32 v63, 0
	v_mov_b32_e32 v64, 0
	v_mov_b32_e32 v65, 0
	v_lshl_add_u64 v[46:47], v[4:5], 0, v[46:47]
	v_cmp_gt_u32_e32 vcc, 0x800, v44
	v_cmp_gt_u32_e64 s[34:35], 16, v7
	s_and_b64 vcc, vcc, s[34:35]
	s_and_saveexec_b64 s[28:29], vcc
	global_load_dwordx4 v[62:65], v[46:47], off
	s_mov_b64 exec, s[28:29]
